# hgrn pass1/pass3 gate maths: denormal pre-scale/post-offset around v_log_f32 removed at 57 sites (arguments never denormal; bit-identical)
# baseline (speedup 1.0000x reference)
.LBB0_312:
	v_sub_f32_e32 v12, 1.0, v7
	s_mov_b64 s[0:1], -1
	s_waitcnt vmcnt(0)
	v_mov_b32_e32 v28, v170
	v_mov_b32_e32 v29, v171
	v_mov_b32_e32 v30, v172
	v_mov_b32_e32 v31, v173
	v_mov_b32_e32 v32, v174
	v_mov_b32_e32 v33, v175
	v_mov_b32_e32 v35, v176
	v_mov_b32_e32 v48, v177
	v_mov_b32_e32 v49, v178
	v_mov_b32_e32 v101, v179
	v_mov_b32_e32 v102, v180
	v_mov_b32_e32 v103, v181
	v_mov_b32_e32 v104, v182
	v_mov_b32_e32 v105, v183
	v_mov_b32_e32 v106, v184
	v_mov_b32_e32 v93, v185
	v_lshlrev_b32_e32 v107, 16, v28
	v_mul_f32_e64 v28, |v107|, s47
	v_exp_f32_e32 v28, v28
	v_cmp_le_f32_e32 vcc, 0, v107
	v_add_f32_e32 v108, 1.0, v28
	v_rcp_f32_e32 v100, v108
	s_nop 0
	v_mul_f32_e32 v28, v28, v100
	v_cndmask_b32_e32 v28, v28, v100, vcc
	s_and_b64 vcc, exec, s[36:37]
	s_cbranch_vccz .LBB0_314
	v_fma_f32 v100, v12, v28, v7
	s_mov_b32 s0, 0x7f800000
	s_nop 0
	v_log_f32_e32 v100, v100
	s_nop 0
	v_mul_f32_e32 v110, 0x3f317217, v100
	v_fma_f32 v110, v100, s24, -v110
	v_fmac_f32_e32 v110, 0x3377d1cf, v100
	v_fmac_f32_e32 v110, 0x3f317217, v100
	v_cmp_lt_f32_e64 vcc, |v100|, s0
	s_mov_b64 s[0:1], 0
	s_nop 0
	v_cndmask_b32_e32 v100, v100, v110, vcc
.LBB0_314:
	s_andn2_b64 vcc, exec, s[0:1]
	s_cbranch_vccnz .LBB0_316
	s_mov_b32 s0, 0x7f800000
	v_max_f32_e64 v107, -v107, -v107
	v_log_f32_e32 v100, v108
	s_nop 0
	v_max_f32_e32 v107, 0, v107
	v_mul_f32_e32 v109, 0x3f317217, v100
	v_fma_f32 v109, v100, s24, -v109
	v_fmac_f32_e32 v109, 0x3377d1cf, v100
	v_fmac_f32_e32 v109, 0x3f317217, v100
	v_cmp_lt_f32_e64 vcc, |v100|, s0
	s_nop 1
	v_cndmask_b32_e32 v100, v100, v109, vcc
	v_add_f32_e32 v100, v107, v100
	v_xor_b32_e32 v100, 0x80000000, v100
.LBB0_316:
	v_lshlrev_b32_e32 v107, 16, v29
	v_mul_f32_e64 v29, |v107|, s47
	v_exp_f32_e32 v29, v29
	v_cndmask_b32_e64 v110, 0, 1, s[36:37]
	v_cmp_le_f32_e64 s[42:43], 0, v107
	v_cmp_ne_u32_e64 s[40:41], 1, v110
	v_add_f32_e32 v109, 1.0, v29
	v_rcp_f32_e32 v108, v109
	s_andn2_b64 vcc, exec, s[36:37]
	s_mov_b64 s[0:1], -1
	v_mul_f32_e32 v29, v29, v108
	v_cndmask_b32_e64 v29, v29, v108, s[42:43]
	s_cbranch_vccnz .LBB0_318
	v_fma_f32 v108, v12, v29, v7
	s_mov_b32 s0, 0x7f800000
	s_nop 0
	v_log_f32_e32 v108, v108
	s_nop 0
	v_mul_f32_e32 v111, 0x3f317217, v108
	v_fma_f32 v111, v108, s24, -v111
	v_fmac_f32_e32 v111, 0x3377d1cf, v108
	v_fmac_f32_e32 v111, 0x3f317217, v108
	v_cmp_lt_f32_e64 vcc, |v108|, s0
	s_mov_b64 s[0:1], 0
	s_nop 0
	v_cndmask_b32_e32 v108, v108, v111, vcc
.LBB0_318:
	s_andn2_b64 vcc, exec, s[0:1]
	s_cbranch_vccnz .LBB0_320
	s_mov_b32 s0, 0x7f800000
	v_max_f32_e64 v107, -v107, -v107
	v_log_f32_e32 v108, v109
	s_nop 0
	v_max_f32_e32 v107, 0, v107
	v_mul_f32_e32 v110, 0x3f317217, v108
	v_fma_f32 v110, v108, s24, -v110
	v_fmac_f32_e32 v110, 0x3377d1cf, v108
	v_fmac_f32_e32 v110, 0x3f317217, v108
	v_cmp_lt_f32_e64 vcc, |v108|, s0
	s_nop 1
	v_cndmask_b32_e32 v108, v108, v110, vcc
	v_add_f32_e32 v107, v107, v108
	v_xor_b32_e32 v108, 0x80000000, v107
.LBB0_320:
	v_lshlrev_b32_e32 v107, 16, v30
	v_mul_f32_e64 v30, |v107|, s47
	v_exp_f32_e32 v30, v30
	v_cmp_le_f32_e64 s[42:43], 0, v107
	s_and_b64 vcc, exec, s[40:41]
	s_mov_b64 s[0:1], -1
	v_add_f32_e32 v110, 1.0, v30
	v_rcp_f32_e32 v109, v110
	s_nop 0
	v_mul_f32_e32 v30, v30, v109
	v_cndmask_b32_e64 v30, v30, v109, s[42:43]
	s_cbranch_vccnz .LBB0_322
	v_fma_f32 v109, v12, v30, v7
	s_mov_b32 s0, 0x7f800000
	s_nop 0
	v_log_f32_e32 v109, v109
	s_nop 0
	v_mul_f32_e32 v112, 0x3f317217, v109
	v_fma_f32 v112, v109, s24, -v112
	v_fmac_f32_e32 v112, 0x3377d1cf, v109
	v_fmac_f32_e32 v112, 0x3f317217, v109
	v_cmp_lt_f32_e64 vcc, |v109|, s0
	s_mov_b64 s[0:1], 0
	s_nop 0
	v_cndmask_b32_e32 v109, v109, v112, vcc
.LBB0_322:
	s_andn2_b64 vcc, exec, s[0:1]
	s_cbranch_vccnz .LBB0_324
	s_mov_b32 s0, 0x7f800000
	v_max_f32_e64 v107, -v107, -v107
	v_log_f32_e32 v109, v110
	s_nop 0
	v_max_f32_e32 v107, 0, v107
	v_mul_f32_e32 v111, 0x3f317217, v109
	v_fma_f32 v111, v109, s24, -v111
	v_fmac_f32_e32 v111, 0x3377d1cf, v109
	v_fmac_f32_e32 v111, 0x3f317217, v109
	v_cmp_lt_f32_e64 vcc, |v109|, s0
	s_nop 1
	v_cndmask_b32_e32 v109, v109, v111, vcc
	v_add_f32_e32 v107, v107, v109
	v_xor_b32_e32 v109, 0x80000000, v107
.LBB0_324:
	v_lshlrev_b32_e32 v107, 16, v31
	v_mul_f32_e64 v31, |v107|, s47
	v_exp_f32_e32 v31, v31
	v_cmp_le_f32_e64 s[42:43], 0, v107
	s_and_b64 vcc, exec, s[40:41]
	s_mov_b64 s[0:1], -1
	v_add_f32_e32 v111, 1.0, v31
	v_rcp_f32_e32 v110, v111
	s_nop 0
	v_mul_f32_e32 v31, v31, v110
	v_cndmask_b32_e64 v31, v31, v110, s[42:43]
	s_cbranch_vccnz .LBB0_326
	v_fma_f32 v110, v12, v31, v7
	s_mov_b32 s0, 0x7f800000
	s_nop 0
	v_log_f32_e32 v110, v110
	s_nop 0
	v_mul_f32_e32 v113, 0x3f317217, v110
	v_fma_f32 v113, v110, s24, -v113
	v_fmac_f32_e32 v113, 0x3377d1cf, v110
	v_fmac_f32_e32 v113, 0x3f317217, v110
	v_cmp_lt_f32_e64 vcc, |v110|, s0
	s_mov_b64 s[0:1], 0
	s_nop 0
	v_cndmask_b32_e32 v110, v110, v113, vcc
.LBB0_326:
	s_andn2_b64 vcc, exec, s[0:1]
	s_cbranch_vccnz .LBB0_328
	s_mov_b32 s0, 0x7f800000
	v_max_f32_e64 v107, -v107, -v107
	v_log_f32_e32 v110, v111
	s_nop 0
	v_max_f32_e32 v107, 0, v107
	v_mul_f32_e32 v112, 0x3f317217, v110
	v_fma_f32 v112, v110, s24, -v112
	v_fmac_f32_e32 v112, 0x3377d1cf, v110
	v_fmac_f32_e32 v112, 0x3f317217, v110
	v_cmp_lt_f32_e64 vcc, |v110|, s0
	s_nop 1
	v_cndmask_b32_e32 v110, v110, v112, vcc
	v_add_f32_e32 v107, v107, v110
	v_xor_b32_e32 v110, 0x80000000, v107
.LBB0_328:
	v_lshlrev_b32_e32 v107, 16, v32
	v_mul_f32_e64 v32, |v107|, s47
	v_exp_f32_e32 v32, v32
	v_cmp_le_f32_e64 s[42:43], 0, v107
	s_and_b64 vcc, exec, s[40:41]
	s_mov_b64 s[0:1], -1
	v_add_f32_e32 v112, 1.0, v32
	v_rcp_f32_e32 v111, v112
	s_nop 0
	v_mul_f32_e32 v32, v32, v111
	v_cndmask_b32_e64 v32, v32, v111, s[42:43]
	s_cbranch_vccnz .LBB0_330
	v_fma_f32 v111, v12, v32, v7
	s_mov_b32 s0, 0x7f800000
	s_nop 0
	v_log_f32_e32 v111, v111
	s_nop 0
	v_mul_f32_e32 v114, 0x3f317217, v111
	v_fma_f32 v114, v111, s24, -v114
	v_fmac_f32_e32 v114, 0x3377d1cf, v111
	v_fmac_f32_e32 v114, 0x3f317217, v111
	v_cmp_lt_f32_e64 vcc, |v111|, s0
	s_mov_b64 s[0:1], 0
	s_nop 0
	v_cndmask_b32_e32 v111, v111, v114, vcc
.LBB0_330:
	s_andn2_b64 vcc, exec, s[0:1]
	s_cbranch_vccnz .LBB0_332
	s_mov_b32 s0, 0x7f800000
	v_max_f32_e64 v107, -v107, -v107
	v_log_f32_e32 v111, v112
	s_nop 0
	v_max_f32_e32 v107, 0, v107
	v_mul_f32_e32 v113, 0x3f317217, v111
	v_fma_f32 v113, v111, s24, -v113
	v_fmac_f32_e32 v113, 0x3377d1cf, v111
	v_fmac_f32_e32 v113, 0x3f317217, v111
	v_cmp_lt_f32_e64 vcc, |v111|, s0
	s_nop 1
	v_cndmask_b32_e32 v111, v111, v113, vcc
	v_add_f32_e32 v107, v107, v111
	v_xor_b32_e32 v111, 0x80000000, v107
.LBB0_332:
	v_lshlrev_b32_e32 v107, 16, v33
	v_mul_f32_e64 v33, |v107|, s47
	v_exp_f32_e32 v33, v33
	v_cmp_le_f32_e64 s[42:43], 0, v107
	s_and_b64 vcc, exec, s[40:41]
	s_mov_b64 s[0:1], -1
	v_add_f32_e32 v113, 1.0, v33
	v_rcp_f32_e32 v112, v113
	s_nop 0
	v_mul_f32_e32 v33, v33, v112
	v_cndmask_b32_e64 v33, v33, v112, s[42:43]
	s_cbranch_vccnz .LBB0_334
	v_fma_f32 v112, v12, v33, v7
	s_mov_b32 s0, 0x7f800000
	s_nop 0
	v_log_f32_e32 v112, v112
	s_nop 0
	v_mul_f32_e32 v115, 0x3f317217, v112
	v_fma_f32 v115, v112, s24, -v115
	v_fmac_f32_e32 v115, 0x3377d1cf, v112
	v_fmac_f32_e32 v115, 0x3f317217, v112
	v_cmp_lt_f32_e64 vcc, |v112|, s0
	s_mov_b64 s[0:1], 0
	s_nop 0
	v_cndmask_b32_e32 v112, v112, v115, vcc
.LBB0_334:
	s_andn2_b64 vcc, exec, s[0:1]
	s_cbranch_vccnz .LBB0_336
	s_mov_b32 s0, 0x7f800000
	v_max_f32_e64 v107, -v107, -v107
	v_log_f32_e32 v112, v113
	s_nop 0
	v_max_f32_e32 v107, 0, v107
	v_mul_f32_e32 v114, 0x3f317217, v112
	v_fma_f32 v114, v112, s24, -v114
	v_fmac_f32_e32 v114, 0x3377d1cf, v112
	v_fmac_f32_e32 v114, 0x3f317217, v112
	v_cmp_lt_f32_e64 vcc, |v112|, s0
	s_nop 1
	v_cndmask_b32_e32 v112, v112, v114, vcc
	v_add_f32_e32 v107, v107, v112
	v_xor_b32_e32 v112, 0x80000000, v107
.LBB0_336:
	v_lshlrev_b32_e32 v107, 16, v35
	v_mul_f32_e64 v35, |v107|, s47
	v_exp_f32_e32 v35, v35
	v_cmp_le_f32_e64 s[42:43], 0, v107
	s_and_b64 vcc, exec, s[40:41]
	s_mov_b64 s[0:1], -1
	v_add_f32_e32 v114, 1.0, v35
	v_rcp_f32_e32 v113, v114
	s_nop 0
	v_mul_f32_e32 v35, v35, v113
	v_cndmask_b32_e64 v35, v35, v113, s[42:43]
	s_cbranch_vccnz .LBB0_338
	v_fma_f32 v113, v12, v35, v7
	s_mov_b32 s0, 0x7f800000
	s_nop 0
	v_log_f32_e32 v113, v113
	s_nop 0
	v_mul_f32_e32 v116, 0x3f317217, v113
	v_fma_f32 v116, v113, s24, -v116
	v_fmac_f32_e32 v116, 0x3377d1cf, v113
	v_fmac_f32_e32 v116, 0x3f317217, v113
	v_cmp_lt_f32_e64 vcc, |v113|, s0
	s_mov_b64 s[0:1], 0
	s_nop 0
	v_cndmask_b32_e32 v113, v113, v116, vcc
.LBB0_338:
	s_andn2_b64 vcc, exec, s[0:1]
	s_cbranch_vccnz .LBB0_340
	s_mov_b32 s0, 0x7f800000
	v_max_f32_e64 v107, -v107, -v107
	v_log_f32_e32 v113, v114
	s_nop 0
	v_max_f32_e32 v107, 0, v107
	v_mul_f32_e32 v115, 0x3f317217, v113
	v_fma_f32 v115, v113, s24, -v115
	v_fmac_f32_e32 v115, 0x3377d1cf, v113
	v_fmac_f32_e32 v115, 0x3f317217, v113
	v_cmp_lt_f32_e64 vcc, |v113|, s0
	s_nop 1
	v_cndmask_b32_e32 v113, v113, v115, vcc
	v_add_f32_e32 v107, v107, v113
	v_xor_b32_e32 v113, 0x80000000, v107
.LBB0_340:
	v_lshlrev_b32_e32 v107, 16, v48
	v_mul_f32_e64 v48, |v107|, s47
	v_exp_f32_e32 v48, v48
	v_cmp_le_f32_e64 s[42:43], 0, v107
	s_and_b64 vcc, exec, s[40:41]
	s_mov_b64 s[0:1], -1
	v_add_f32_e32 v115, 1.0, v48
	v_rcp_f32_e32 v114, v115
	s_nop 0
	v_mul_f32_e32 v48, v48, v114
	v_cndmask_b32_e64 v48, v48, v114, s[42:43]
	s_cbranch_vccnz .LBB0_342
	v_fma_f32 v114, v12, v48, v7
	s_mov_b32 s0, 0x7f800000
	s_nop 0
	v_log_f32_e32 v114, v114
	s_nop 0
	v_mul_f32_e32 v117, 0x3f317217, v114
	v_fma_f32 v117, v114, s24, -v117
	v_fmac_f32_e32 v117, 0x3377d1cf, v114
	v_fmac_f32_e32 v117, 0x3f317217, v114
	v_cmp_lt_f32_e64 vcc, |v114|, s0
	s_mov_b64 s[0:1], 0
	s_nop 0
	v_cndmask_b32_e32 v114, v114, v117, vcc
.LBB0_342:
	s_andn2_b64 vcc, exec, s[0:1]
	s_cbranch_vccnz .LBB0_344
	s_mov_b32 s0, 0x7f800000
	v_max_f32_e64 v107, -v107, -v107
	v_log_f32_e32 v114, v115
	s_nop 0
	v_max_f32_e32 v107, 0, v107
	v_mul_f32_e32 v116, 0x3f317217, v114
	v_fma_f32 v116, v114, s24, -v116
	v_fmac_f32_e32 v116, 0x3377d1cf, v114
	v_fmac_f32_e32 v116, 0x3f317217, v114
	v_cmp_lt_f32_e64 vcc, |v114|, s0
	s_nop 1
	v_cndmask_b32_e32 v114, v114, v116, vcc
	v_add_f32_e32 v107, v107, v114
	v_xor_b32_e32 v114, 0x80000000, v107
.LBB0_344:
	v_lshlrev_b32_e32 v107, 16, v49
	v_mul_f32_e64 v49, |v107|, s47
	v_exp_f32_e32 v49, v49
	v_cmp_le_f32_e64 s[42:43], 0, v107
	s_and_b64 vcc, exec, s[40:41]
	s_mov_b64 s[0:1], -1
	v_add_f32_e32 v116, 1.0, v49
	v_rcp_f32_e32 v115, v116
	s_nop 0
	v_mul_f32_e32 v49, v49, v115
	v_cndmask_b32_e64 v49, v49, v115, s[42:43]
	s_cbranch_vccnz .LBB0_346
	v_fma_f32 v115, v12, v49, v7
	s_mov_b32 s0, 0x7f800000
	s_nop 0
	v_log_f32_e32 v115, v115
	s_nop 0
	v_mul_f32_e32 v118, 0x3f317217, v115
	v_fma_f32 v118, v115, s24, -v118
	v_fmac_f32_e32 v118, 0x3377d1cf, v115
	v_fmac_f32_e32 v118, 0x3f317217, v115
	v_cmp_lt_f32_e64 vcc, |v115|, s0
	s_mov_b64 s[0:1], 0
	s_nop 0
	v_cndmask_b32_e32 v115, v115, v118, vcc
.LBB0_346:
	s_andn2_b64 vcc, exec, s[0:1]
	s_cbranch_vccnz .LBB0_348
	s_mov_b32 s0, 0x7f800000
	v_max_f32_e64 v107, -v107, -v107
	v_log_f32_e32 v115, v116
	s_nop 0
	v_max_f32_e32 v107, 0, v107
	v_mul_f32_e32 v117, 0x3f317217, v115
	v_fma_f32 v117, v115, s24, -v117
	v_fmac_f32_e32 v117, 0x3377d1cf, v115
	v_fmac_f32_e32 v117, 0x3f317217, v115
	v_cmp_lt_f32_e64 vcc, |v115|, s0
	s_nop 1
	v_cndmask_b32_e32 v115, v115, v117, vcc
	v_add_f32_e32 v107, v107, v115
	v_xor_b32_e32 v115, 0x80000000, v107

.LBB0_350:
	s_andn2_b64 vcc, exec, s[0:1]
	s_cbranch_vccnz .LBB0_352
	s_mov_b32 s0, 0x7f800000
	v_max_f32_e64 v107, -v107, -v107
	v_log_f32_e32 v116, v116
	s_nop 0
	v_max_f32_e32 v107, 0, v107
	v_mul_f32_e32 v118, 0x3f317217, v116
	v_fma_f32 v118, v116, s24, -v118
	v_fmac_f32_e32 v118, 0x3377d1cf, v116
	v_fmac_f32_e32 v118, 0x3f317217, v116
	v_cmp_lt_f32_e64 vcc, |v116|, s0
	s_nop 1
	v_cndmask_b32_e32 v116, v116, v118, vcc
	v_add_f32_e32 v107, v107, v116
	v_xor_b32_e32 v119, 0x80000000, v107

.LBB0_354:
	s_andn2_b64 vcc, exec, s[0:1]
	s_cbranch_vccnz .LBB0_356
	s_mov_b32 s0, 0x7f800000
	v_max_f32_e64 v107, -v107, -v107
	v_log_f32_e32 v116, v116
	s_nop 0
	v_max_f32_e32 v107, 0, v107
	v_mul_f32_e32 v118, 0x3f317217, v116
	v_fma_f32 v118, v116, s24, -v118
	v_fmac_f32_e32 v118, 0x3377d1cf, v116
	v_fmac_f32_e32 v118, 0x3f317217, v116
	v_cmp_lt_f32_e64 vcc, |v116|, s0
	s_nop 1
	v_cndmask_b32_e32 v116, v116, v118, vcc
	v_add_f32_e32 v107, v107, v116
	v_xor_b32_e32 v121, 0x80000000, v107

.LBB0_358:
	s_andn2_b64 vcc, exec, s[0:1]
	s_cbranch_vccnz .LBB0_360
	s_mov_b32 s0, 0x7f800000
	v_max_f32_e64 v107, -v107, -v107
	v_log_f32_e32 v116, v116
	s_nop 0
	v_max_f32_e32 v107, 0, v107
	v_mul_f32_e32 v118, 0x3f317217, v116
	v_fma_f32 v118, v116, s24, -v118
	v_fmac_f32_e32 v118, 0x3377d1cf, v116
	v_fmac_f32_e32 v118, 0x3f317217, v116
	v_cmp_lt_f32_e64 vcc, |v116|, s0
	s_nop 1
	v_cndmask_b32_e32 v116, v116, v118, vcc
	v_add_f32_e32 v107, v107, v116
	v_xor_b32_e32 v123, 0x80000000, v107

.LBB0_362:
	s_andn2_b64 vcc, exec, s[0:1]
	s_cbranch_vccnz .LBB0_364
	s_mov_b32 s0, 0x7f800000
	v_max_f32_e64 v107, -v107, -v107
	v_log_f32_e32 v116, v116
	s_nop 0
	v_max_f32_e32 v107, 0, v107
	v_mul_f32_e32 v118, 0x3f317217, v116
	v_fma_f32 v118, v116, s24, -v118
	v_fmac_f32_e32 v118, 0x3377d1cf, v116
	v_fmac_f32_e32 v118, 0x3f317217, v116
	v_cmp_lt_f32_e64 vcc, |v116|, s0
	s_nop 1
	v_cndmask_b32_e32 v116, v116, v118, vcc
	v_add_f32_e32 v107, v107, v116
	v_xor_b32_e32 v125, 0x80000000, v107

.LBB0_366:
	s_andn2_b64 vcc, exec, s[0:1]
	s_cbranch_vccnz .LBB0_368
	s_mov_b32 s0, 0x7f800000
	v_max_f32_e64 v107, -v107, -v107
	v_log_f32_e32 v116, v116
	s_nop 0
	v_max_f32_e32 v107, 0, v107
	v_mul_f32_e32 v118, 0x3f317217, v116
	v_fma_f32 v118, v116, s24, -v118
	v_fmac_f32_e32 v118, 0x3377d1cf, v116
	v_fmac_f32_e32 v118, 0x3f317217, v116
	v_cmp_lt_f32_e64 vcc, |v116|, s0
	s_nop 1
	v_cndmask_b32_e32 v116, v116, v118, vcc
	v_add_f32_e32 v107, v107, v116
	v_xor_b32_e32 v127, 0x80000000, v107

.LBB0_370:
	s_andn2_b64 vcc, exec, s[0:1]
	s_cbranch_vccnz .LBB0_372
	s_mov_b32 s0, 0x7f800000
	v_max_f32_e64 v106, -v106, -v106
	v_log_f32_e32 v116, v116
	s_nop 0
	v_max_f32_e32 v106, 0, v106
	v_mul_f32_e32 v118, 0x3f317217, v116
	v_fma_f32 v118, v116, s24, -v118
	v_fmac_f32_e32 v118, 0x3377d1cf, v116
	v_fmac_f32_e32 v118, 0x3f317217, v116
	v_cmp_lt_f32_e64 vcc, |v116|, s0
	s_nop 1
	v_cndmask_b32_e32 v116, v116, v118, vcc
	v_add_f32_e32 v106, v106, v116
	v_xor_b32_e32 v129, 0x80000000, v106

.LBB0_374:
	s_andn2_b64 vcc, exec, s[0:1]
	s_cbranch_vccnz .LBB0_376
	s_mov_b32 s0, 0x7f800000
	v_max_f32_e64 v93, -v93, -v93
	v_log_f32_e32 v7, v116
	s_nop 0
	v_max_f32_e32 v93, 0, v93
	v_mul_f32_e32 v117, 0x3f317217, v7
	v_fma_f32 v117, v7, s24, -v117
	v_fmac_f32_e32 v117, 0x3377d1cf, v7
	v_fmac_f32_e32 v117, 0x3f317217, v7
	v_cmp_lt_f32_e64 vcc, |v7|, s0
	s_nop 1
	v_cndmask_b32_e32 v7, v7, v117, vcc
	v_add_f32_e32 v7, v93, v7
	v_xor_b32_e32 v131, 0x80000000, v7

.LBB0_461:
	v_mov_b32_e32 v134, v208
	s_movk_i32 s2, 0x81
	v_subrev_u32_e32 v0, 64, v134
	v_cmp_gt_u32_e32 vcc, s2, v0
	v_mov_b32_e32 v41, 0
	s_and_saveexec_b64 s[2:3], vcc
	s_cbranch_execz .LBB0_465
	s_movk_i32 s4, 0x4f
	v_cmp_lt_u32_e32 vcc, s4, v134
	s_and_saveexec_b64 s[4:5], vcc
	s_cbranch_execz .LBB0_464
	v_cvt_f32_u32_e32 v0, v0
	s_mov_b32 s11, 0x7f800000
	v_mul_f32_e32 v0, 0x3d800000, v0
	s_nop 1
	v_log_f32_e32 v0, v0
	s_nop 0
	v_mul_f32_e32 v3, 0x3f317217, v0
	v_fma_f32 v3, v0, s24, -v3
	v_fmac_f32_e32 v3, 0x3377d1cf, v0
	v_fmac_f32_e32 v3, 0x3f317217, v0
	v_cmp_lt_f32_e64 vcc, |v0|, s11
	s_mov_b32 s11, 0x40051592
	s_nop 0
	v_cndmask_b32_e32 v0, v0, v3, vcc
	v_div_scale_f32 v2, s[12:13], s11, s11, v0
	v_rcp_f32_e32 v3, v2
	v_div_scale_f32 v4, vcc, v0, s11, v0
	v_fma_f32 v5, -v2, v3, 1.0
	v_fmac_f32_e32 v3, v5, v3
	v_mul_f32_e32 v5, v4, v3
	v_fma_f32 v6, -v2, v5, v4
	v_fmac_f32_e32 v5, v6, v3
	v_fma_f32 v2, -v2, v5, v4
	v_div_fmas_f32 v2, v2, v3, v5
	v_div_fixup_f32 v0, v2, s11, v0
	v_mul_f32_e32 v0, 0x41800000, v0
	v_cvt_i32_f32_e32 v0, v0
	v_min_i32_e32 v0, 15, v0
	v_add_u32_e32 v0, 16, v0

.LBB0_538:
	v_ashrrev_i32_e32 v4, 7, v2
	s_lshl_b32 s54, s2, 1
	v_sub_f32_e32 v0, 1.0, v5
	s_mov_b64 s[0:1], -1
	s_waitcnt vmcnt(0)
	v_mov_b32_e32 v7, v100
	v_mov_b32_e32 v11, v101
	v_mov_b32_e32 v15, v102
	v_mov_b32_e32 v16, v103
	v_mov_b32_e32 v34, v104
	v_mov_b32_e32 v38, v105
	v_mov_b32_e32 v41, v106
	v_mov_b32_e32 v44, v107
	v_mov_b32_e32 v45, v108
	v_mov_b32_e32 v42, v109
	v_mov_b32_e32 v39, v110
	v_mov_b32_e32 v36, v111
	v_mov_b32_e32 v17, v112
	v_mov_b32_e32 v9, v113
	v_mov_b32_e32 v8, v114
	v_mov_b32_e32 v6, v115
	v_lshlrev_b32_e32 v14, 16, v7
	v_mul_f32_e64 v7, |v14|, s47
	v_exp_f32_e32 v7, v7
	v_cmp_le_f32_e32 vcc, 0, v14
	v_add_f32_e32 v35, 1.0, v7
	v_rcp_f32_e32 v10, v35
	s_nop 0
	v_mul_f32_e32 v7, v7, v10
	v_cndmask_b32_e32 v10, v7, v10, vcc
	s_and_b64 vcc, exec, s[48:49]
	s_cbranch_vccz .LBB0_540
	v_fma_f32 v7, v0, v10, v5
	s_mov_b32 s0, 0x7f800000
	s_nop 0
	v_log_f32_e32 v7, v7
	s_nop 0
	v_mul_f32_e32 v40, 0x3f317217, v7
	v_fma_f32 v40, v7, s24, -v40
	v_fmac_f32_e32 v40, 0x3377d1cf, v7
	v_fmac_f32_e32 v40, 0x3f317217, v7
	v_cmp_lt_f32_e64 vcc, |v7|, s0
	s_mov_b64 s[0:1], 0
	s_nop 0
	v_cndmask_b32_e32 v7, v7, v40, vcc
.LBB0_540:
	s_andn2_b64 vcc, exec, s[0:1]
	s_cbranch_vccnz .LBB0_542
	s_mov_b32 s0, 0x7f800000
	v_max_f32_e64 v14, -v14, -v14
	v_log_f32_e32 v7, v35
	s_nop 0
	v_max_f32_e32 v14, 0, v14
	v_mul_f32_e32 v37, 0x3f317217, v7
	v_fma_f32 v37, v7, s24, -v37
	v_fmac_f32_e32 v37, 0x3377d1cf, v7
	v_fmac_f32_e32 v37, 0x3f317217, v7
	v_cmp_lt_f32_e64 vcc, |v7|, s0
	s_nop 1
	v_cndmask_b32_e32 v7, v7, v37, vcc
	v_add_f32_e32 v7, v14, v7
	v_xor_b32_e32 v7, 0x80000000, v7
.LBB0_542:
	v_lshlrev_b32_e32 v35, 16, v11
	v_mul_f32_e64 v11, |v35|, s47
	v_exp_f32_e32 v11, v11
	v_cndmask_b32_e64 v40, 0, 1, s[48:49]
	v_cmp_le_f32_e64 s[42:43], 0, v35
	v_cmp_ne_u32_e64 s[40:41], 1, v40
	v_add_f32_e32 v37, 1.0, v11
	v_rcp_f32_e32 v14, v37
	s_andn2_b64 vcc, exec, s[48:49]
	s_mov_b64 s[0:1], -1
	v_mul_f32_e32 v11, v11, v14
	v_cndmask_b32_e64 v14, v11, v14, s[42:43]
	s_cbranch_vccnz .LBB0_544
	v_fma_f32 v11, v0, v14, v5
	s_mov_b32 s0, 0x7f800000
	s_nop 0
	v_log_f32_e32 v11, v11
	s_nop 0
	v_mul_f32_e32 v43, 0x3f317217, v11
	v_fma_f32 v43, v11, s24, -v43
	v_fmac_f32_e32 v43, 0x3377d1cf, v11
	v_fmac_f32_e32 v43, 0x3f317217, v11
	v_cmp_lt_f32_e64 vcc, |v11|, s0
	s_mov_b64 s[0:1], 0
	s_nop 0
	v_cndmask_b32_e32 v11, v11, v43, vcc
.LBB0_544:
	s_andn2_b64 vcc, exec, s[0:1]
	s_cbranch_vccnz .LBB0_546
	s_mov_b32 s0, 0x7f800000
	v_max_f32_e64 v35, -v35, -v35
	v_log_f32_e32 v11, v37
	s_nop 0
	v_max_f32_e32 v35, 0, v35
	v_mul_f32_e32 v40, 0x3f317217, v11
	v_fma_f32 v40, v11, s24, -v40
	v_fmac_f32_e32 v40, 0x3377d1cf, v11
	v_fmac_f32_e32 v40, 0x3f317217, v11
	v_cmp_lt_f32_e64 vcc, |v11|, s0
	s_nop 1
	v_cndmask_b32_e32 v11, v11, v40, vcc
	v_add_f32_e32 v11, v35, v11
	v_xor_b32_e32 v11, 0x80000000, v11
.LBB0_546:
	v_lshlrev_b32_e32 v37, 16, v15
	v_mul_f32_e64 v15, |v37|, s47
	v_exp_f32_e32 v15, v15
	v_cmp_le_f32_e64 s[42:43], 0, v37
	s_and_b64 vcc, exec, s[40:41]
	s_mov_b64 s[0:1], -1
	v_add_f32_e32 v40, 1.0, v15
	v_rcp_f32_e32 v35, v40
	s_nop 0
	v_mul_f32_e32 v15, v15, v35
	v_cndmask_b32_e64 v15, v15, v35, s[42:43]
	s_cbranch_vccnz .LBB0_548
	v_fma_f32 v35, v0, v15, v5
	s_mov_b32 s0, 0x7f800000
	s_nop 0
	v_log_f32_e32 v35, v35
	s_nop 0
	v_mul_f32_e32 v46, 0x3f317217, v35
	v_fma_f32 v46, v35, s24, -v46
	v_fmac_f32_e32 v46, 0x3377d1cf, v35
	v_fmac_f32_e32 v46, 0x3f317217, v35
	v_cmp_lt_f32_e64 vcc, |v35|, s0
	s_mov_b64 s[0:1], 0
	s_nop 0
	v_cndmask_b32_e32 v35, v35, v46, vcc
.LBB0_548:
	s_andn2_b64 vcc, exec, s[0:1]
	s_cbranch_vccnz .LBB0_550
	s_mov_b32 s0, 0x7f800000
	v_max_f32_e64 v37, -v37, -v37
	v_log_f32_e32 v35, v40
	s_nop 0
	v_max_f32_e32 v37, 0, v37
	v_mul_f32_e32 v43, 0x3f317217, v35
	v_fma_f32 v43, v35, s24, -v43
	v_fmac_f32_e32 v43, 0x3377d1cf, v35
	v_fmac_f32_e32 v43, 0x3f317217, v35
	v_cmp_lt_f32_e64 vcc, |v35|, s0
	s_nop 1
	v_cndmask_b32_e32 v35, v35, v43, vcc
	v_add_f32_e32 v35, v37, v35
	v_xor_b32_e32 v35, 0x80000000, v35
.LBB0_550:
	v_lshlrev_b32_e32 v40, 16, v16
	v_mul_f32_e64 v16, |v40|, s47
	v_exp_f32_e32 v16, v16
	v_cmp_le_f32_e64 s[42:43], 0, v40
	s_and_b64 vcc, exec, s[40:41]
	s_mov_b64 s[0:1], -1
	v_add_f32_e32 v43, 1.0, v16
	v_rcp_f32_e32 v37, v43
	s_nop 0
	v_mul_f32_e32 v16, v16, v37
	v_cndmask_b32_e64 v16, v16, v37, s[42:43]
	s_cbranch_vccnz .LBB0_552
	v_fma_f32 v37, v0, v16, v5
	s_mov_b32 s0, 0x7f800000
	s_nop 0
	v_log_f32_e32 v37, v37
	s_nop 0
	v_mul_f32_e32 v47, 0x3f317217, v37
	v_fma_f32 v47, v37, s24, -v47
	v_fmac_f32_e32 v47, 0x3377d1cf, v37
	v_fmac_f32_e32 v47, 0x3f317217, v37
	v_cmp_lt_f32_e64 vcc, |v37|, s0
	s_mov_b64 s[0:1], 0
	s_nop 0
	v_cndmask_b32_e32 v37, v37, v47, vcc
.LBB0_552:
	s_andn2_b64 vcc, exec, s[0:1]
	s_cbranch_vccnz .LBB0_554
	s_mov_b32 s0, 0x7f800000
	v_max_f32_e64 v40, -v40, -v40
	v_log_f32_e32 v37, v43
	s_nop 0
	v_max_f32_e32 v40, 0, v40
	v_mul_f32_e32 v46, 0x3f317217, v37
	v_fma_f32 v46, v37, s24, -v46
	v_fmac_f32_e32 v46, 0x3377d1cf, v37
	v_fmac_f32_e32 v46, 0x3f317217, v37
	v_cmp_lt_f32_e64 vcc, |v37|, s0
	s_nop 1
	v_cndmask_b32_e32 v37, v37, v46, vcc
	v_add_f32_e32 v37, v40, v37
	v_xor_b32_e32 v37, 0x80000000, v37
.LBB0_554:
	v_lshlrev_b32_e32 v43, 16, v34
	v_mul_f32_e64 v34, |v43|, s47
	v_exp_f32_e32 v34, v34
	v_cmp_le_f32_e64 s[42:43], 0, v43
	s_and_b64 vcc, exec, s[40:41]
	s_mov_b64 s[0:1], -1
	v_add_f32_e32 v46, 1.0, v34
	v_rcp_f32_e32 v40, v46
	s_nop 0
	v_mul_f32_e32 v34, v34, v40
	v_cndmask_b32_e64 v34, v34, v40, s[42:43]
	s_cbranch_vccnz .LBB0_556
	v_fma_f32 v40, v0, v34, v5
	s_mov_b32 s0, 0x7f800000
	s_nop 0
	v_log_f32_e32 v40, v40
	s_nop 0
	v_mul_f32_e32 v48, 0x3f317217, v40
	v_fma_f32 v48, v40, s24, -v48
	v_fmac_f32_e32 v48, 0x3377d1cf, v40
	v_fmac_f32_e32 v48, 0x3f317217, v40
	v_cmp_lt_f32_e64 vcc, |v40|, s0
	s_mov_b64 s[0:1], 0
	s_nop 0
	v_cndmask_b32_e32 v40, v40, v48, vcc
.LBB0_556:
	s_andn2_b64 vcc, exec, s[0:1]
	s_cbranch_vccnz .LBB0_558
	s_mov_b32 s0, 0x7f800000
	v_max_f32_e64 v43, -v43, -v43
	v_log_f32_e32 v40, v46
	s_nop 0
	v_max_f32_e32 v43, 0, v43
	v_mul_f32_e32 v47, 0x3f317217, v40
	v_fma_f32 v47, v40, s24, -v47
	v_fmac_f32_e32 v47, 0x3377d1cf, v40
	v_fmac_f32_e32 v47, 0x3f317217, v40
	v_cmp_lt_f32_e64 vcc, |v40|, s0
	s_nop 1
	v_cndmask_b32_e32 v40, v40, v47, vcc
	v_add_f32_e32 v40, v43, v40
	v_xor_b32_e32 v40, 0x80000000, v40
.LBB0_558:
	v_lshlrev_b32_e32 v46, 16, v38
	v_mul_f32_e64 v38, |v46|, s47
	v_exp_f32_e32 v38, v38
	v_cmp_le_f32_e64 s[42:43], 0, v46
	s_and_b64 vcc, exec, s[40:41]
	s_mov_b64 s[0:1], -1
	v_add_f32_e32 v47, 1.0, v38
	v_rcp_f32_e32 v43, v47
	s_nop 0
	v_mul_f32_e32 v38, v38, v43
	v_cndmask_b32_e64 v38, v38, v43, s[42:43]
	s_cbranch_vccnz .LBB0_560
	v_fma_f32 v43, v0, v38, v5
	s_mov_b32 s0, 0x7f800000
	s_nop 0
	v_log_f32_e32 v43, v43
	s_nop 0
	v_mul_f32_e32 v49, 0x3f317217, v43
	v_fma_f32 v49, v43, s24, -v49
	v_fmac_f32_e32 v49, 0x3377d1cf, v43
	v_fmac_f32_e32 v49, 0x3f317217, v43
	v_cmp_lt_f32_e64 vcc, |v43|, s0
	s_mov_b64 s[0:1], 0
	s_nop 0
	v_cndmask_b32_e32 v43, v43, v49, vcc
.LBB0_560:
	s_andn2_b64 vcc, exec, s[0:1]
	s_cbranch_vccnz .LBB0_562
	s_mov_b32 s0, 0x7f800000
	v_max_f32_e64 v46, -v46, -v46
	v_log_f32_e32 v43, v47
	s_nop 0
	v_max_f32_e32 v46, 0, v46
	v_mul_f32_e32 v48, 0x3f317217, v43
	v_fma_f32 v48, v43, s24, -v48
	v_fmac_f32_e32 v48, 0x3377d1cf, v43
	v_fmac_f32_e32 v48, 0x3f317217, v43
	v_cmp_lt_f32_e64 vcc, |v43|, s0
	s_nop 1
	v_cndmask_b32_e32 v43, v43, v48, vcc
	v_add_f32_e32 v43, v46, v43
	v_xor_b32_e32 v43, 0x80000000, v43
.LBB0_562:
	v_lshlrev_b32_e32 v47, 16, v41
	v_mul_f32_e64 v41, |v47|, s47
	v_exp_f32_e32 v41, v41
	v_cmp_le_f32_e64 s[42:43], 0, v47
	s_and_b64 vcc, exec, s[40:41]
	s_mov_b64 s[0:1], -1
	v_add_f32_e32 v48, 1.0, v41
	v_rcp_f32_e32 v46, v48
	s_nop 0
	v_mul_f32_e32 v41, v41, v46
	v_cndmask_b32_e64 v41, v41, v46, s[42:43]
	s_cbranch_vccnz .LBB0_564
	v_fma_f32 v46, v0, v41, v5
	s_mov_b32 s0, 0x7f800000
	s_nop 0
	v_log_f32_e32 v46, v46
	s_nop 0
	v_mul_f32_e32 v50, 0x3f317217, v46
	v_fma_f32 v50, v46, s24, -v50
	v_fmac_f32_e32 v50, 0x3377d1cf, v46
	v_fmac_f32_e32 v50, 0x3f317217, v46
	v_cmp_lt_f32_e64 vcc, |v46|, s0
	s_mov_b64 s[0:1], 0
	s_nop 0
	v_cndmask_b32_e32 v46, v46, v50, vcc
.LBB0_564:
	s_andn2_b64 vcc, exec, s[0:1]
	s_cbranch_vccnz .LBB0_566
	s_mov_b32 s0, 0x7f800000
	v_max_f32_e64 v47, -v47, -v47
	v_log_f32_e32 v46, v48
	s_nop 0
	v_max_f32_e32 v47, 0, v47
	v_mul_f32_e32 v49, 0x3f317217, v46
	v_fma_f32 v49, v46, s24, -v49
	v_fmac_f32_e32 v49, 0x3377d1cf, v46
	v_fmac_f32_e32 v49, 0x3f317217, v46
	v_cmp_lt_f32_e64 vcc, |v46|, s0
	s_nop 1
	v_cndmask_b32_e32 v46, v46, v49, vcc
	v_add_f32_e32 v46, v47, v46
	v_xor_b32_e32 v46, 0x80000000, v46
.LBB0_566:
	v_lshlrev_b32_e32 v48, 16, v44
	v_mul_f32_e64 v44, |v48|, s47
	v_exp_f32_e32 v44, v44
	v_cmp_le_f32_e64 s[42:43], 0, v48
	s_and_b64 vcc, exec, s[40:41]
	s_mov_b64 s[0:1], -1
	v_add_f32_e32 v49, 1.0, v44
	v_rcp_f32_e32 v47, v49
	s_nop 0
	v_mul_f32_e32 v44, v44, v47
	v_cndmask_b32_e64 v44, v44, v47, s[42:43]
	s_cbranch_vccnz .LBB0_568
	v_fma_f32 v47, v0, v44, v5
	s_mov_b32 s0, 0x7f800000
	s_nop 0
	v_log_f32_e32 v47, v47
	s_nop 0
	v_mul_f32_e32 v51, 0x3f317217, v47
	v_fma_f32 v51, v47, s24, -v51
	v_fmac_f32_e32 v51, 0x3377d1cf, v47
	v_fmac_f32_e32 v51, 0x3f317217, v47
	v_cmp_lt_f32_e64 vcc, |v47|, s0
	s_mov_b64 s[0:1], 0
	s_nop 0
	v_cndmask_b32_e32 v47, v47, v51, vcc
.LBB0_568:
	s_andn2_b64 vcc, exec, s[0:1]
	s_cbranch_vccnz .LBB0_570
	s_mov_b32 s0, 0x7f800000
	v_max_f32_e64 v48, -v48, -v48
	v_log_f32_e32 v47, v49
	s_nop 0
	v_max_f32_e32 v48, 0, v48
	v_mul_f32_e32 v50, 0x3f317217, v47
	v_fma_f32 v50, v47, s24, -v50
	v_fmac_f32_e32 v50, 0x3377d1cf, v47
	v_fmac_f32_e32 v50, 0x3f317217, v47
	v_cmp_lt_f32_e64 vcc, |v47|, s0
	s_nop 1
	v_cndmask_b32_e32 v47, v47, v50, vcc
	v_add_f32_e32 v47, v48, v47
	v_xor_b32_e32 v47, 0x80000000, v47
.LBB0_570:
	v_lshlrev_b32_e32 v49, 16, v45
	v_mul_f32_e64 v45, |v49|, s47
	v_exp_f32_e32 v45, v45
	v_cmp_le_f32_e64 s[42:43], 0, v49
	s_and_b64 vcc, exec, s[40:41]
	s_mov_b64 s[0:1], -1
	v_add_f32_e32 v50, 1.0, v45
	v_rcp_f32_e32 v48, v50
	s_nop 0
	v_mul_f32_e32 v45, v45, v48
	v_cndmask_b32_e64 v45, v45, v48, s[42:43]
	s_cbranch_vccnz .LBB0_572
	v_fma_f32 v48, v0, v45, v5
	s_mov_b32 s0, 0x7f800000
	s_nop 0
	v_log_f32_e32 v48, v48
	s_nop 0
	v_mul_f32_e32 v52, 0x3f317217, v48
	v_fma_f32 v52, v48, s24, -v52
	v_fmac_f32_e32 v52, 0x3377d1cf, v48
	v_fmac_f32_e32 v52, 0x3f317217, v48
	v_cmp_lt_f32_e64 vcc, |v48|, s0
	s_mov_b64 s[0:1], 0
	s_nop 0
	v_cndmask_b32_e32 v48, v48, v52, vcc
.LBB0_572:
	s_andn2_b64 vcc, exec, s[0:1]
	s_cbranch_vccnz .LBB0_574
	s_mov_b32 s0, 0x7f800000
	v_max_f32_e64 v49, -v49, -v49
	v_log_f32_e32 v48, v50
	s_nop 0
	v_max_f32_e32 v49, 0, v49
	v_mul_f32_e32 v51, 0x3f317217, v48
	v_fma_f32 v51, v48, s24, -v51
	v_fmac_f32_e32 v51, 0x3377d1cf, v48
	v_fmac_f32_e32 v51, 0x3f317217, v48
	v_cmp_lt_f32_e64 vcc, |v48|, s0
	s_nop 1
	v_cndmask_b32_e32 v48, v48, v51, vcc
	v_add_f32_e32 v48, v49, v48
	v_xor_b32_e32 v48, 0x80000000, v48
.LBB0_574:
	v_lshlrev_b32_e32 v50, 16, v42
	v_mul_f32_e64 v42, |v50|, s47
	v_exp_f32_e32 v42, v42
	v_cmp_le_f32_e64 s[42:43], 0, v50
	s_and_b64 vcc, exec, s[40:41]
	s_mov_b64 s[0:1], -1
	v_add_f32_e32 v51, 1.0, v42
	v_rcp_f32_e32 v49, v51
	s_nop 0
	v_mul_f32_e32 v42, v42, v49
	v_cndmask_b32_e64 v42, v42, v49, s[42:43]
	s_cbranch_vccnz .LBB0_576
	v_fma_f32 v49, v0, v42, v5
	s_mov_b32 s0, 0x7f800000
	s_nop 0
	v_log_f32_e32 v49, v49
	s_nop 0
	v_mul_f32_e32 v53, 0x3f317217, v49
	v_fma_f32 v53, v49, s24, -v53
	v_fmac_f32_e32 v53, 0x3377d1cf, v49
	v_fmac_f32_e32 v53, 0x3f317217, v49
	v_cmp_lt_f32_e64 vcc, |v49|, s0
	s_mov_b64 s[0:1], 0
	s_nop 0
	v_cndmask_b32_e32 v49, v49, v53, vcc
.LBB0_576:
	s_andn2_b64 vcc, exec, s[0:1]
	s_cbranch_vccnz .LBB0_578
	s_mov_b32 s0, 0x7f800000
	v_max_f32_e64 v50, -v50, -v50
	v_log_f32_e32 v49, v51
	s_nop 0
	v_max_f32_e32 v50, 0, v50
	v_mul_f32_e32 v52, 0x3f317217, v49
	v_fma_f32 v52, v49, s24, -v52
	v_fmac_f32_e32 v52, 0x3377d1cf, v49
	v_fmac_f32_e32 v52, 0x3f317217, v49
	v_cmp_lt_f32_e64 vcc, |v49|, s0
	s_nop 1
	v_cndmask_b32_e32 v49, v49, v52, vcc
	v_add_f32_e32 v49, v50, v49
	v_xor_b32_e32 v49, 0x80000000, v49
.LBB0_578:
	v_lshlrev_b32_e32 v51, 16, v39
	v_mul_f32_e64 v39, |v51|, s47
	v_exp_f32_e32 v39, v39
	v_cmp_le_f32_e64 s[42:43], 0, v51
	s_and_b64 vcc, exec, s[40:41]
	s_mov_b64 s[0:1], -1
	v_add_f32_e32 v52, 1.0, v39
	v_rcp_f32_e32 v50, v52
	s_nop 0
	v_mul_f32_e32 v39, v39, v50
	v_cndmask_b32_e64 v39, v39, v50, s[42:43]
	s_cbranch_vccnz .LBB0_580
	v_fma_f32 v50, v0, v39, v5
	s_mov_b32 s0, 0x7f800000
	s_nop 0
	v_log_f32_e32 v50, v50
	s_nop 0
	v_mul_f32_e32 v54, 0x3f317217, v50
	v_fma_f32 v54, v50, s24, -v54
	v_fmac_f32_e32 v54, 0x3377d1cf, v50
	v_fmac_f32_e32 v54, 0x3f317217, v50
	v_cmp_lt_f32_e64 vcc, |v50|, s0
	s_mov_b64 s[0:1], 0
	s_nop 0
	v_cndmask_b32_e32 v50, v50, v54, vcc
.LBB0_580:
	s_andn2_b64 vcc, exec, s[0:1]
	s_cbranch_vccnz .LBB0_582
	s_mov_b32 s0, 0x7f800000
	v_max_f32_e64 v51, -v51, -v51
	v_log_f32_e32 v50, v52
	s_nop 0
	v_max_f32_e32 v51, 0, v51
	v_mul_f32_e32 v53, 0x3f317217, v50
	v_fma_f32 v53, v50, s24, -v53
	v_fmac_f32_e32 v53, 0x3377d1cf, v50
	v_fmac_f32_e32 v53, 0x3f317217, v50
	v_cmp_lt_f32_e64 vcc, |v50|, s0
	s_nop 1
	v_cndmask_b32_e32 v50, v50, v53, vcc
	v_add_f32_e32 v50, v51, v50
	v_xor_b32_e32 v50, 0x80000000, v50
.LBB0_582:
	v_lshlrev_b32_e32 v52, 16, v36
	v_mul_f32_e64 v36, |v52|, s47
	v_exp_f32_e32 v36, v36
	v_cmp_le_f32_e64 s[42:43], 0, v52
	s_and_b64 vcc, exec, s[40:41]
	s_mov_b64 s[0:1], -1
	v_add_f32_e32 v53, 1.0, v36
	v_rcp_f32_e32 v51, v53
	s_nop 0
	v_mul_f32_e32 v36, v36, v51
	v_cndmask_b32_e64 v36, v36, v51, s[42:43]
	s_cbranch_vccnz .LBB0_584
	v_fma_f32 v51, v0, v36, v5
	s_mov_b32 s0, 0x7f800000
	s_nop 0
	v_log_f32_e32 v51, v51
	s_nop 0
	v_mul_f32_e32 v55, 0x3f317217, v51
	v_fma_f32 v55, v51, s24, -v55
	v_fmac_f32_e32 v55, 0x3377d1cf, v51
	v_fmac_f32_e32 v55, 0x3f317217, v51
	v_cmp_lt_f32_e64 vcc, |v51|, s0
	s_mov_b64 s[0:1], 0
	s_nop 0
	v_cndmask_b32_e32 v51, v51, v55, vcc
.LBB0_584:
	s_andn2_b64 vcc, exec, s[0:1]
	s_cbranch_vccnz .LBB0_586
	s_mov_b32 s0, 0x7f800000
	v_max_f32_e64 v52, -v52, -v52
	v_log_f32_e32 v51, v53
	s_nop 0
	v_max_f32_e32 v52, 0, v52
	v_mul_f32_e32 v54, 0x3f317217, v51
	v_fma_f32 v54, v51, s24, -v54
	v_fmac_f32_e32 v54, 0x3377d1cf, v51
	v_fmac_f32_e32 v54, 0x3f317217, v51
	v_cmp_lt_f32_e64 vcc, |v51|, s0
	s_nop 1
	v_cndmask_b32_e32 v51, v51, v54, vcc
	v_add_f32_e32 v51, v52, v51
	v_xor_b32_e32 v51, 0x80000000, v51
.LBB0_586:
	v_lshlrev_b32_e32 v52, 16, v17
	v_mul_f32_e64 v17, |v52|, s47
	v_exp_f32_e32 v17, v17
	v_cmp_le_f32_e64 s[42:43], 0, v52
	s_and_b64 vcc, exec, s[40:41]
	s_mov_b64 s[0:1], -1
	v_add_f32_e32 v54, 1.0, v17
	v_rcp_f32_e32 v53, v54
	s_nop 0
	v_mul_f32_e32 v17, v17, v53
	v_cndmask_b32_e64 v17, v17, v53, s[42:43]
	s_cbranch_vccnz .LBB0_588
	v_fma_f32 v53, v0, v17, v5
	s_mov_b32 s0, 0x7f800000
	s_nop 0
	v_log_f32_e32 v53, v53
	s_nop 0
	v_mul_f32_e32 v56, 0x3f317217, v53
	v_fma_f32 v56, v53, s24, -v56
	v_fmac_f32_e32 v56, 0x3377d1cf, v53
	v_fmac_f32_e32 v56, 0x3f317217, v53
	v_cmp_lt_f32_e64 vcc, |v53|, s0
	s_mov_b64 s[0:1], 0
	s_nop 0
	v_cndmask_b32_e32 v53, v53, v56, vcc
.LBB0_588:
	s_andn2_b64 vcc, exec, s[0:1]
	s_cbranch_vccnz .LBB0_590
	s_mov_b32 s0, 0x7f800000
	v_max_f32_e64 v52, -v52, -v52
	v_log_f32_e32 v53, v54
	s_nop 0
	v_max_f32_e32 v52, 0, v52
	v_mul_f32_e32 v55, 0x3f317217, v53
	v_fma_f32 v55, v53, s24, -v55
	v_fmac_f32_e32 v55, 0x3377d1cf, v53
	v_fmac_f32_e32 v55, 0x3f317217, v53
	v_cmp_lt_f32_e64 vcc, |v53|, s0
	s_nop 1
	v_cndmask_b32_e32 v53, v53, v55, vcc
	v_add_f32_e32 v52, v52, v53
	v_xor_b32_e32 v53, 0x80000000, v52
.LBB0_590:
	v_lshlrev_b32_e32 v54, 16, v9
	v_mul_f32_e64 v9, |v54|, s47
	v_exp_f32_e32 v9, v9
	v_cmp_le_f32_e64 s[42:43], 0, v54
	s_and_b64 vcc, exec, s[40:41]
	s_mov_b64 s[0:1], -1
	v_add_f32_e32 v55, 1.0, v9
	v_rcp_f32_e32 v52, v55
	s_nop 0
	v_mul_f32_e32 v9, v9, v52
	v_cndmask_b32_e64 v52, v9, v52, s[42:43]
	s_cbranch_vccnz .LBB0_592
	v_fma_f32 v9, v0, v52, v5
	s_mov_b32 s0, 0x7f800000
	s_nop 0
	v_log_f32_e32 v9, v9
	s_nop 0
	v_mul_f32_e32 v57, 0x3f317217, v9
	v_fma_f32 v57, v9, s24, -v57
	v_fmac_f32_e32 v57, 0x3377d1cf, v9
	v_fmac_f32_e32 v57, 0x3f317217, v9
	v_cmp_lt_f32_e64 vcc, |v9|, s0
	s_mov_b64 s[0:1], 0
	s_nop 0
	v_cndmask_b32_e32 v9, v9, v57, vcc
.LBB0_592:
	s_andn2_b64 vcc, exec, s[0:1]
	s_cbranch_vccnz .LBB0_594
	s_mov_b32 s0, 0x7f800000
	v_max_f32_e64 v54, -v54, -v54
	v_log_f32_e32 v9, v55
	s_nop 0
	v_max_f32_e32 v54, 0, v54
	v_mul_f32_e32 v56, 0x3f317217, v9
	v_fma_f32 v56, v9, s24, -v56
	v_fmac_f32_e32 v56, 0x3377d1cf, v9
	v_fmac_f32_e32 v56, 0x3f317217, v9
	v_cmp_lt_f32_e64 vcc, |v9|, s0
	s_nop 1
	v_cndmask_b32_e32 v9, v9, v56, vcc
	v_add_f32_e32 v9, v54, v9
	v_xor_b32_e32 v9, 0x80000000, v9
.LBB0_594:
	v_lshlrev_b32_e32 v55, 16, v8
	v_mul_f32_e64 v8, |v55|, s47
	v_exp_f32_e32 v8, v8
	v_cmp_le_f32_e64 s[42:43], 0, v55
	s_and_b64 vcc, exec, s[40:41]
	s_mov_b64 s[0:1], -1
	v_add_f32_e32 v56, 1.0, v8
	v_rcp_f32_e32 v54, v56
	s_nop 0
	v_mul_f32_e32 v8, v8, v54
	v_cndmask_b32_e64 v54, v8, v54, s[42:43]
	s_cbranch_vccnz .LBB0_596
	v_fma_f32 v8, v0, v54, v5
	s_mov_b32 s0, 0x7f800000
	s_nop 0
	v_log_f32_e32 v8, v8
	s_nop 0
	v_mul_f32_e32 v58, 0x3f317217, v8
	v_fma_f32 v58, v8, s24, -v58
	v_fmac_f32_e32 v58, 0x3377d1cf, v8
	v_fmac_f32_e32 v58, 0x3f317217, v8
	v_cmp_lt_f32_e64 vcc, |v8|, s0
	s_mov_b64 s[0:1], 0
	s_nop 0
	v_cndmask_b32_e32 v8, v8, v58, vcc
.LBB0_596:
	s_andn2_b64 vcc, exec, s[0:1]
	s_cbranch_vccnz .LBB0_598
	s_mov_b32 s0, 0x7f800000
	v_max_f32_e64 v55, -v55, -v55
	v_log_f32_e32 v8, v56
	s_nop 0
	v_max_f32_e32 v55, 0, v55
	v_mul_f32_e32 v57, 0x3f317217, v8
	v_fma_f32 v57, v8, s24, -v57
	v_fmac_f32_e32 v57, 0x3377d1cf, v8
	v_fmac_f32_e32 v57, 0x3f317217, v8
	v_cmp_lt_f32_e64 vcc, |v8|, s0
	s_nop 1
	v_cndmask_b32_e32 v8, v8, v57, vcc
	v_add_f32_e32 v8, v55, v8
	v_xor_b32_e32 v8, 0x80000000, v8

.LBB0_600:
	s_andn2_b64 vcc, exec, s[0:1]
	s_cbranch_vccnz .LBB0_602
	s_mov_b32 s0, 0x7f800000
	v_max_f32_e64 v6, -v6, -v6
	v_log_f32_e32 v5, v56
	s_nop 0
	v_max_f32_e32 v6, 0, v6
	v_mul_f32_e32 v57, 0x3f317217, v5
	v_fma_f32 v57, v5, s24, -v57
	v_fmac_f32_e32 v57, 0x3377d1cf, v5
	v_fmac_f32_e32 v57, 0x3f317217, v5
	v_cmp_lt_f32_e64 vcc, |v5|, s0
	s_nop 1
	v_cndmask_b32_e32 v5, v5, v57, vcc
	v_add_f32_e32 v5, v6, v5
	v_xor_b32_e32 v62, 0x80000000, v5
